# GEMM unit start accumulator zero-fill uses 64 v_mov_b64 instead of 128 v_mov_b32, on the v77 stack
# speedup vs baseline: 1.0173x; 1.0077x over previous
; template <class Epi, class Sched, bool ALIGN_EPI = false, bool SP2 = false>
; __device__ __forceinline__ void gemm_phase(PG8_LAS unsigned char* lds, const Gemm g, const Sched& S, const Epi& E) {
;     ...
; #pragma unroll
;         for (int a = 0; a < 2; ++a)
; #pragma unroll
;             for (int b = 0; b < 2; ++b)
; #pragma unroll
;                 for (int m = 0; m < 4; ++m)
; #pragma unroll
;                     for (int n = 0; n < 2; ++n) acc[a][b][m][n] = (f32x4){0.f, 0.f, 0.f, 0.f};
;         cur = nxt; cA = nA; cB = nB; ++ui;
.Lzs_17:
	v_mov_b64_e32 v[0:1], 0
	v_mov_b64_e32 v[2:3], 0
	v_mov_b64_e32 v[4:5], 0
	v_mov_b64_e32 v[6:7], 0
	v_mov_b64_e32 v[8:9], 0
	v_mov_b64_e32 v[10:11], 0
	v_mov_b64_e32 v[12:13], 0
	v_mov_b64_e32 v[14:15], 0
	v_mov_b64_e32 v[16:17], 0
	v_mov_b64_e32 v[18:19], 0
	v_mov_b64_e32 v[20:21], 0
	v_mov_b64_e32 v[22:23], 0
	v_mov_b64_e32 v[24:25], 0
	v_mov_b64_e32 v[26:27], 0
	v_mov_b64_e32 v[28:29], 0
	v_mov_b64_e32 v[30:31], 0
	v_mov_b64_e32 v[32:33], 0
	v_mov_b64_e32 v[34:35], 0
	v_mov_b64_e32 v[36:37], 0
	v_mov_b64_e32 v[38:39], 0
	v_mov_b64_e32 v[40:41], 0
	v_mov_b64_e32 v[42:43], 0
	v_mov_b64_e32 v[44:45], 0
	v_mov_b64_e32 v[46:47], 0
	v_mov_b64_e32 v[48:49], 0
	v_mov_b64_e32 v[50:51], 0
	v_mov_b64_e32 v[52:53], 0
	v_mov_b64_e32 v[54:55], 0
	v_mov_b64_e32 v[56:57], 0
	v_mov_b64_e32 v[58:59], 0
	v_mov_b64_e32 v[60:61], 0
	v_mov_b64_e32 v[62:63], 0
	v_mov_b64_e32 v[64:65], 0
	v_mov_b64_e32 v[66:67], 0
	v_mov_b64_e32 v[68:69], 0
	v_mov_b64_e32 v[70:71], 0
	v_mov_b64_e32 v[72:73], 0
	v_mov_b64_e32 v[74:75], 0
	v_mov_b64_e32 v[76:77], 0
	v_mov_b64_e32 v[78:79], 0
	v_mov_b64_e32 v[80:81], 0
	v_mov_b64_e32 v[82:83], 0
	v_mov_b64_e32 v[84:85], 0
	v_mov_b64_e32 v[86:87], 0
	v_mov_b64_e32 v[88:89], 0
	v_mov_b64_e32 v[90:91], 0
	v_mov_b64_e32 v[92:93], 0
	v_mov_b64_e32 v[94:95], 0
	v_mov_b64_e32 v[96:97], 0
	v_mov_b64_e32 v[98:99], 0
	v_mov_b64_e32 v[100:101], 0
	v_mov_b64_e32 v[102:103], 0
	v_mov_b64_e32 v[104:105], 0
	v_mov_b64_e32 v[106:107], 0
	v_mov_b64_e32 v[108:109], 0
	v_mov_b64_e32 v[110:111], 0
	v_mov_b64_e32 v[112:113], 0
	v_mov_b64_e32 v[114:115], 0
	v_mov_b64_e32 v[116:117], 0
	v_mov_b64_e32 v[118:119], 0
	v_mov_b64_e32 v[120:121], 0
	v_mov_b64_e32 v[122:123], 0
	v_mov_b64_e32 v[124:125], 0
	v_mov_b64_e32 v[126:127], 0
	v_lshl_add_u64 v[158:159], v[158:159], 0, s[26:27]
	v_lshl_add_u64 v[160:161], v[160:161], 0, s[22:23]
	s_mov_b32 s10, 0
	.p2align	6

; template <class Epi, class Sched, bool ALIGN_EPI = false, bool SP2 = false>
; __device__ __forceinline__ void gemm_phase(PG8_LAS unsigned char* lds, const Gemm g, const Sched& S, const Epi& E) {
;     ...
; #pragma unroll
;         for (int a = 0; a < 2; ++a)
; #pragma unroll
;             for (int b = 0; b < 2; ++b)
; #pragma unroll
;                 for (int m = 0; m < 4; ++m)
; #pragma unroll
;                     for (int n = 0; n < 2; ++n) acc[a][b][m][n] = (f32x4){0.f, 0.f, 0.f, 0.f};
;         cur = nxt; cA = nA; cB = nB; ++ui;
.Lzs_16:
	v_mov_b64_e32 v[4:5], 0
	v_mov_b64_e32 v[6:7], 0
	v_mov_b64_e32 v[8:9], 0
	v_mov_b64_e32 v[10:11], 0
	v_mov_b64_e32 v[12:13], 0
	v_mov_b64_e32 v[14:15], 0
	v_mov_b64_e32 v[16:17], 0
	v_mov_b64_e32 v[18:19], 0
	v_mov_b64_e32 v[20:21], 0
	v_mov_b64_e32 v[22:23], 0
	v_mov_b64_e32 v[24:25], 0
	v_mov_b64_e32 v[26:27], 0
	v_mov_b64_e32 v[28:29], 0
	v_mov_b64_e32 v[30:31], 0
	v_mov_b64_e32 v[32:33], 0
	v_mov_b64_e32 v[34:35], 0
	v_mov_b64_e32 v[36:37], 0
	v_mov_b64_e32 v[38:39], 0
	v_mov_b64_e32 v[40:41], 0
	v_mov_b64_e32 v[42:43], 0
	v_mov_b64_e32 v[44:45], 0
	v_mov_b64_e32 v[46:47], 0
	v_mov_b64_e32 v[48:49], 0
	v_mov_b64_e32 v[50:51], 0
	v_mov_b64_e32 v[52:53], 0
	v_mov_b64_e32 v[54:55], 0
	v_mov_b64_e32 v[56:57], 0
	v_mov_b64_e32 v[58:59], 0
	v_mov_b64_e32 v[60:61], 0
	v_mov_b64_e32 v[62:63], 0
	v_mov_b64_e32 v[64:65], 0
	v_mov_b64_e32 v[66:67], 0
	v_mov_b64_e32 v[68:69], 0
	v_mov_b64_e32 v[70:71], 0
	v_mov_b64_e32 v[72:73], 0
	v_mov_b64_e32 v[74:75], 0
	v_mov_b64_e32 v[76:77], 0
	v_mov_b64_e32 v[78:79], 0
	v_mov_b64_e32 v[80:81], 0
	v_mov_b64_e32 v[82:83], 0
	v_mov_b64_e32 v[84:85], 0
	v_mov_b64_e32 v[86:87], 0
	v_mov_b64_e32 v[88:89], 0
	v_mov_b64_e32 v[90:91], 0
	v_mov_b64_e32 v[92:93], 0
	v_mov_b64_e32 v[94:95], 0
	v_mov_b64_e32 v[96:97], 0
	v_mov_b64_e32 v[98:99], 0
	v_mov_b64_e32 v[100:101], 0
	v_mov_b64_e32 v[102:103], 0
	v_mov_b64_e32 v[104:105], 0
	v_mov_b64_e32 v[106:107], 0
	v_mov_b64_e32 v[108:109], 0
	v_mov_b64_e32 v[110:111], 0
	v_mov_b64_e32 v[112:113], 0
	v_mov_b64_e32 v[114:115], 0
	v_mov_b64_e32 v[116:117], 0
	v_mov_b64_e32 v[118:119], 0
	v_mov_b64_e32 v[120:121], 0
	v_mov_b64_e32 v[122:123], 0
	v_mov_b64_e32 v[124:125], 0
	v_mov_b64_e32 v[126:127], 0
	v_mov_b64_e32 v[128:129], 0
	v_mov_b64_e32 v[130:131], 0
	v_lshl_add_u64 v[132:133], v[132:133], 0, s[26:27]
	v_lshl_add_u64 v[134:135], v[134:135], 0, s[22:23]
	s_mov_b32 s12, 0
	.p2align	6

; template <class Epi, class Sched, bool ALIGN_EPI = false, bool SP2 = false>
; __device__ __forceinline__ void gemm_phase(PG8_LAS unsigned char* lds, const Gemm g, const Sched& S, const Epi& E) {
;     ...
; #pragma unroll
;         for (int a = 0; a < 2; ++a)
; #pragma unroll
;             for (int b = 0; b < 2; ++b)
; #pragma unroll
;                 for (int m = 0; m < 4; ++m)
; #pragma unroll
;                     for (int n = 0; n < 2; ++n) acc[a][b][m][n] = (f32x4){0.f, 0.f, 0.f, 0.f};
;         cur = nxt; cA = nA; cB = nB; ++ui;
.Lzs_15:
	v_mov_b64_e32 v[0:1], 0
	v_mov_b64_e32 v[2:3], 0
	v_mov_b64_e32 v[4:5], 0
	v_mov_b64_e32 v[6:7], 0
	v_mov_b64_e32 v[8:9], 0
	v_mov_b64_e32 v[10:11], 0
	v_mov_b64_e32 v[12:13], 0
	v_mov_b64_e32 v[14:15], 0
	v_mov_b64_e32 v[16:17], 0
	v_mov_b64_e32 v[18:19], 0
	v_mov_b64_e32 v[20:21], 0
	v_mov_b64_e32 v[22:23], 0
	v_mov_b64_e32 v[24:25], 0
	v_mov_b64_e32 v[26:27], 0
	v_mov_b64_e32 v[28:29], 0
	v_mov_b64_e32 v[30:31], 0
	v_mov_b64_e32 v[32:33], 0
	v_mov_b64_e32 v[34:35], 0
	v_mov_b64_e32 v[36:37], 0
	v_mov_b64_e32 v[38:39], 0
	v_mov_b64_e32 v[40:41], 0
	v_mov_b64_e32 v[42:43], 0
	v_mov_b64_e32 v[44:45], 0
	v_mov_b64_e32 v[46:47], 0
	v_mov_b64_e32 v[48:49], 0
	v_mov_b64_e32 v[50:51], 0
	v_mov_b64_e32 v[52:53], 0
	v_mov_b64_e32 v[54:55], 0
	v_mov_b64_e32 v[56:57], 0
	v_mov_b64_e32 v[58:59], 0
	v_mov_b64_e32 v[60:61], 0
	v_mov_b64_e32 v[62:63], 0
	v_mov_b64_e32 v[64:65], 0
	v_mov_b64_e32 v[66:67], 0
	v_mov_b64_e32 v[68:69], 0
	v_mov_b64_e32 v[70:71], 0
	v_mov_b64_e32 v[72:73], 0
	v_mov_b64_e32 v[74:75], 0
	v_mov_b64_e32 v[76:77], 0
	v_mov_b64_e32 v[78:79], 0
	v_mov_b64_e32 v[80:81], 0
	v_mov_b64_e32 v[82:83], 0
	v_mov_b64_e32 v[84:85], 0
	v_mov_b64_e32 v[86:87], 0
	v_mov_b64_e32 v[88:89], 0
	v_mov_b64_e32 v[90:91], 0
	v_mov_b64_e32 v[92:93], 0
	v_mov_b64_e32 v[94:95], 0
	v_mov_b64_e32 v[96:97], 0
	v_mov_b64_e32 v[98:99], 0
	v_mov_b64_e32 v[100:101], 0
	v_mov_b64_e32 v[102:103], 0
	v_mov_b64_e32 v[104:105], 0
	v_mov_b64_e32 v[106:107], 0
	v_mov_b64_e32 v[108:109], 0
	v_mov_b64_e32 v[110:111], 0
	v_mov_b64_e32 v[112:113], 0
	v_mov_b64_e32 v[114:115], 0
	v_mov_b64_e32 v[116:117], 0
	v_mov_b64_e32 v[118:119], 0
	v_mov_b64_e32 v[120:121], 0
	v_mov_b64_e32 v[122:123], 0
	v_mov_b64_e32 v[124:125], 0
	v_mov_b64_e32 v[126:127], 0
	v_lshl_add_u64 v[128:129], v[128:129], 0, s[34:35]
	v_lshl_add_u64 v[130:131], v[130:131], 0, s[24:25]
	s_mov_b32 s12, 0
	.p2align	6

; template <class Epi, class Sched, bool ALIGN_EPI = false, bool SP2 = false>
; __device__ __forceinline__ void gemm_phase(PG8_LAS unsigned char* lds, const Gemm g, const Sched& S, const Epi& E) {
;     ...
; #pragma unroll
;         for (int a = 0; a < 2; ++a)
; #pragma unroll
;             for (int b = 0; b < 2; ++b)
; #pragma unroll
;                 for (int m = 0; m < 4; ++m)
; #pragma unroll
;                     for (int n = 0; n < 2; ++n) acc[a][b][m][n] = (f32x4){0.f, 0.f, 0.f, 0.f};
;         cur = nxt; cA = nA; cB = nB; ++ui;
.Lzs_14:
	v_mov_b64_e32 v[0:1], 0
	v_mov_b64_e32 v[2:3], 0
	v_mov_b64_e32 v[4:5], 0
	v_mov_b64_e32 v[6:7], 0
	v_mov_b64_e32 v[8:9], 0
	v_mov_b64_e32 v[10:11], 0
	v_mov_b64_e32 v[12:13], 0
	v_mov_b64_e32 v[14:15], 0
	v_mov_b64_e32 v[16:17], 0
	v_mov_b64_e32 v[18:19], 0
	v_mov_b64_e32 v[20:21], 0
	v_mov_b64_e32 v[22:23], 0
	v_mov_b64_e32 v[24:25], 0
	v_mov_b64_e32 v[26:27], 0
	v_mov_b64_e32 v[28:29], 0
	v_mov_b64_e32 v[30:31], 0
	v_mov_b64_e32 v[32:33], 0
	v_mov_b64_e32 v[34:35], 0
	v_mov_b64_e32 v[36:37], 0
	v_mov_b64_e32 v[38:39], 0
	v_mov_b64_e32 v[40:41], 0
	v_mov_b64_e32 v[42:43], 0
	v_mov_b64_e32 v[44:45], 0
	v_mov_b64_e32 v[46:47], 0
	v_mov_b64_e32 v[48:49], 0
	v_mov_b64_e32 v[50:51], 0
	v_mov_b64_e32 v[52:53], 0
	v_mov_b64_e32 v[54:55], 0
	v_mov_b64_e32 v[56:57], 0
	v_mov_b64_e32 v[58:59], 0
	v_mov_b64_e32 v[60:61], 0
	v_mov_b64_e32 v[62:63], 0
	v_mov_b64_e32 v[64:65], 0
	v_mov_b64_e32 v[66:67], 0
	v_mov_b64_e32 v[68:69], 0
	v_mov_b64_e32 v[70:71], 0
	v_mov_b64_e32 v[72:73], 0
	v_mov_b64_e32 v[74:75], 0
	v_mov_b64_e32 v[76:77], 0
	v_mov_b64_e32 v[78:79], 0
	v_mov_b64_e32 v[80:81], 0
	v_mov_b64_e32 v[82:83], 0
	v_mov_b64_e32 v[84:85], 0
	v_mov_b64_e32 v[86:87], 0
	v_mov_b64_e32 v[96:97], 0
	v_mov_b64_e32 v[98:99], 0
	v_mov_b64_e32 v[100:101], 0
	v_mov_b64_e32 v[102:103], 0
	v_mov_b64_e32 v[104:105], 0
	v_mov_b64_e32 v[106:107], 0
	v_mov_b64_e32 v[108:109], 0
	v_mov_b64_e32 v[110:111], 0
	v_mov_b64_e32 v[112:113], 0
	v_mov_b64_e32 v[114:115], 0
	v_mov_b64_e32 v[116:117], 0
	v_mov_b64_e32 v[118:119], 0
	v_mov_b64_e32 v[120:121], 0
	v_mov_b64_e32 v[122:123], 0
	v_mov_b64_e32 v[124:125], 0
	v_mov_b64_e32 v[126:127], 0
	v_mov_b64_e32 v[136:137], 0
	v_mov_b64_e32 v[138:139], 0
	v_mov_b64_e32 v[140:141], 0
	v_mov_b64_e32 v[142:143], 0
	v_lshl_add_u64 v[88:89], v[88:89], 0, s[30:31]
	v_lshl_add_u64 v[90:91], v[90:91], 0, s[24:25]
	s_mov_b32 s10, 0
	.p2align	6

; template <class Epi, class Sched, bool ALIGN_EPI = false, bool SP2 = false>
; __device__ __forceinline__ void gemm_phase(PG8_LAS unsigned char* lds, const Gemm g, const Sched& S, const Epi& E) {
;     ...
; #pragma unroll
;         for (int a = 0; a < 2; ++a)
; #pragma unroll
;             for (int b = 0; b < 2; ++b)
; #pragma unroll
;                 for (int m = 0; m < 4; ++m)
; #pragma unroll
;                     for (int n = 0; n < 2; ++n) acc[a][b][m][n] = (f32x4){0.f, 0.f, 0.f, 0.f};
;         cur = nxt; cA = nA; cB = nB; ++ui;
.Lzs_13:
	v_mov_b64_e32 v[0:1], 0
	v_mov_b64_e32 v[2:3], 0
	v_mov_b64_e32 v[4:5], 0
	v_mov_b64_e32 v[6:7], 0
	v_mov_b64_e32 v[8:9], 0
	v_mov_b64_e32 v[10:11], 0
	v_mov_b64_e32 v[12:13], 0
	v_mov_b64_e32 v[14:15], 0
	v_mov_b64_e32 v[16:17], 0
	v_mov_b64_e32 v[18:19], 0
	v_mov_b64_e32 v[20:21], 0
	v_mov_b64_e32 v[22:23], 0
	v_mov_b64_e32 v[24:25], 0
	v_mov_b64_e32 v[26:27], 0
	v_mov_b64_e32 v[28:29], 0
	v_mov_b64_e32 v[30:31], 0
	v_mov_b64_e32 v[32:33], 0
	v_mov_b64_e32 v[34:35], 0
	v_mov_b64_e32 v[36:37], 0
	v_mov_b64_e32 v[38:39], 0
	v_mov_b64_e32 v[40:41], 0
	v_mov_b64_e32 v[42:43], 0
	v_mov_b64_e32 v[44:45], 0
	v_mov_b64_e32 v[46:47], 0
	v_mov_b64_e32 v[48:49], 0
	v_mov_b64_e32 v[50:51], 0
	v_mov_b64_e32 v[52:53], 0
	v_mov_b64_e32 v[54:55], 0
	v_mov_b64_e32 v[56:57], 0
	v_mov_b64_e32 v[58:59], 0
	v_mov_b64_e32 v[60:61], 0
	v_mov_b64_e32 v[62:63], 0
	v_mov_b64_e32 v[64:65], 0
	v_mov_b64_e32 v[66:67], 0
	v_mov_b64_e32 v[68:69], 0
	v_mov_b64_e32 v[70:71], 0
	v_mov_b64_e32 v[72:73], 0
	v_mov_b64_e32 v[74:75], 0
	v_mov_b64_e32 v[76:77], 0
	v_mov_b64_e32 v[78:79], 0
	v_mov_b64_e32 v[80:81], 0
	v_mov_b64_e32 v[82:83], 0
	v_mov_b64_e32 v[84:85], 0
	v_mov_b64_e32 v[86:87], 0
	v_mov_b64_e32 v[88:89], 0
	v_mov_b64_e32 v[90:91], 0
	v_mov_b64_e32 v[92:93], 0
	v_mov_b64_e32 v[94:95], 0
	v_mov_b64_e32 v[96:97], 0
	v_mov_b64_e32 v[98:99], 0
	v_mov_b64_e32 v[100:101], 0
	v_mov_b64_e32 v[102:103], 0
	v_mov_b64_e32 v[104:105], 0
	v_mov_b64_e32 v[106:107], 0
	v_mov_b64_e32 v[108:109], 0
	v_mov_b64_e32 v[110:111], 0
	v_mov_b64_e32 v[120:121], 0
	v_mov_b64_e32 v[122:123], 0
	v_mov_b64_e32 v[124:125], 0
	v_mov_b64_e32 v[126:127], 0
	v_mov_b64_e32 v[128:129], 0
	v_mov_b64_e32 v[130:131], 0
	v_mov_b64_e32 v[132:133], 0
	v_mov_b64_e32 v[134:135], 0
	v_lshl_add_u64 v[112:113], v[112:113], 0, s[26:27]
	v_lshl_add_u64 v[114:115], v[114:115], 0, s[18:19]
	s_mov_b32 s8, 0
	.p2align	6

; template <class Epi, class Sched, bool ALIGN_EPI = false, bool SP2 = false>
; __device__ __forceinline__ void gemm_phase(PG8_LAS unsigned char* lds, const Gemm g, const Sched& S, const Epi& E) {
;     ...
; #pragma unroll
;         for (int a = 0; a < 2; ++a)
; #pragma unroll
;             for (int b = 0; b < 2; ++b)
; #pragma unroll
;                 for (int m = 0; m < 4; ++m)
; #pragma unroll
;                     for (int n = 0; n < 2; ++n) acc[a][b][m][n] = (f32x4){0.f, 0.f, 0.f, 0.f};
;         cur = nxt; cA = nA; cB = nB; ++ui;
.Lzs_12:
	v_mov_b64_e32 v[0:1], 0
	v_mov_b64_e32 v[2:3], 0
	v_mov_b64_e32 v[4:5], 0
	v_mov_b64_e32 v[6:7], 0
	v_mov_b64_e32 v[8:9], 0
	v_mov_b64_e32 v[10:11], 0
	v_mov_b64_e32 v[12:13], 0
	v_mov_b64_e32 v[14:15], 0
	v_mov_b64_e32 v[16:17], 0
	v_mov_b64_e32 v[18:19], 0
	v_mov_b64_e32 v[20:21], 0
	v_mov_b64_e32 v[22:23], 0
	v_mov_b64_e32 v[24:25], 0
	v_mov_b64_e32 v[26:27], 0
	v_mov_b64_e32 v[28:29], 0
	v_mov_b64_e32 v[30:31], 0
	v_mov_b64_e32 v[32:33], 0
	v_mov_b64_e32 v[34:35], 0
	v_mov_b64_e32 v[36:37], 0
	v_mov_b64_e32 v[38:39], 0
	v_mov_b64_e32 v[40:41], 0
	v_mov_b64_e32 v[42:43], 0
	v_mov_b64_e32 v[44:45], 0
	v_mov_b64_e32 v[46:47], 0
	v_mov_b64_e32 v[48:49], 0
	v_mov_b64_e32 v[50:51], 0
	v_mov_b64_e32 v[52:53], 0
	v_mov_b64_e32 v[54:55], 0
	v_mov_b64_e32 v[56:57], 0
	v_mov_b64_e32 v[58:59], 0
	v_mov_b64_e32 v[60:61], 0
	v_mov_b64_e32 v[62:63], 0
	v_mov_b64_e32 v[64:65], 0
	v_mov_b64_e32 v[66:67], 0
	v_mov_b64_e32 v[68:69], 0
	v_mov_b64_e32 v[70:71], 0
	v_mov_b64_e32 v[72:73], 0
	v_mov_b64_e32 v[74:75], 0
	v_mov_b64_e32 v[76:77], 0
	v_mov_b64_e32 v[78:79], 0
	v_mov_b64_e32 v[80:81], 0
	v_mov_b64_e32 v[82:83], 0
	v_mov_b64_e32 v[84:85], 0
	v_mov_b64_e32 v[86:87], 0
	v_mov_b64_e32 v[88:89], 0
	v_mov_b64_e32 v[90:91], 0
	v_mov_b64_e32 v[92:93], 0
	v_mov_b64_e32 v[94:95], 0
	v_mov_b64_e32 v[96:97], 0
	v_mov_b64_e32 v[98:99], 0
	v_mov_b64_e32 v[100:101], 0
	v_mov_b64_e32 v[102:103], 0
	v_mov_b64_e32 v[104:105], 0
	v_mov_b64_e32 v[106:107], 0
	v_mov_b64_e32 v[108:109], 0
	v_mov_b64_e32 v[110:111], 0
	v_mov_b64_e32 v[112:113], 0
	v_mov_b64_e32 v[114:115], 0
	v_mov_b64_e32 v[116:117], 0
	v_mov_b64_e32 v[118:119], 0
	v_mov_b64_e32 v[120:121], 0
	v_mov_b64_e32 v[122:123], 0
	v_mov_b64_e32 v[124:125], 0
	v_mov_b64_e32 v[126:127], 0
	v_lshl_add_u64 v[128:129], v[128:129], 0, s[26:27]
	v_lshl_add_u64 v[130:131], v[130:131], 0, s[22:23]
	s_mov_b32 s12, 0
	.p2align	6

; template <class Epi, class Sched, bool ALIGN_EPI = false, bool SP2 = false>
; __device__ __forceinline__ void gemm_phase(PG8_LAS unsigned char* lds, const Gemm g, const Sched& S, const Epi& E) {
;     ...
; #pragma unroll
;         for (int a = 0; a < 2; ++a)
; #pragma unroll
;             for (int b = 0; b < 2; ++b)
; #pragma unroll
;                 for (int m = 0; m < 4; ++m)
; #pragma unroll
;                     for (int n = 0; n < 2; ++n) acc[a][b][m][n] = (f32x4){0.f, 0.f, 0.f, 0.f};
;         cur = nxt; cA = nA; cB = nB; ++ui;
.Lzs_9:
	v_mov_b64_e32 v[0:1], 0
	v_mov_b64_e32 v[2:3], 0
	v_mov_b64_e32 v[4:5], 0
	v_mov_b64_e32 v[6:7], 0
	v_mov_b64_e32 v[8:9], 0
	v_mov_b64_e32 v[10:11], 0
	v_mov_b64_e32 v[12:13], 0
	v_mov_b64_e32 v[14:15], 0
	v_mov_b64_e32 v[16:17], 0
	v_mov_b64_e32 v[18:19], 0
	v_mov_b64_e32 v[20:21], 0
	v_mov_b64_e32 v[22:23], 0
	v_mov_b64_e32 v[24:25], 0
	v_mov_b64_e32 v[26:27], 0
	v_mov_b64_e32 v[28:29], 0
	v_mov_b64_e32 v[30:31], 0
	v_mov_b64_e32 v[32:33], 0
	v_mov_b64_e32 v[34:35], 0
	v_mov_b64_e32 v[36:37], 0
	v_mov_b64_e32 v[38:39], 0
	v_mov_b64_e32 v[40:41], 0
	v_mov_b64_e32 v[42:43], 0
	v_mov_b64_e32 v[44:45], 0
	v_mov_b64_e32 v[46:47], 0
	v_mov_b64_e32 v[48:49], 0
	v_mov_b64_e32 v[50:51], 0
	v_mov_b64_e32 v[52:53], 0
	v_mov_b64_e32 v[54:55], 0
	v_mov_b64_e32 v[56:57], 0
	v_mov_b64_e32 v[58:59], 0
	v_mov_b64_e32 v[60:61], 0
	v_mov_b64_e32 v[62:63], 0
	v_mov_b64_e32 v[64:65], 0
	v_mov_b64_e32 v[66:67], 0
	v_mov_b64_e32 v[68:69], 0
	v_mov_b64_e32 v[70:71], 0
	v_mov_b64_e32 v[72:73], 0
	v_mov_b64_e32 v[74:75], 0
	v_mov_b64_e32 v[76:77], 0
	v_mov_b64_e32 v[78:79], 0
	v_mov_b64_e32 v[80:81], 0
	v_mov_b64_e32 v[82:83], 0
	v_mov_b64_e32 v[84:85], 0
	v_mov_b64_e32 v[86:87], 0
	v_mov_b64_e32 v[88:89], 0
	v_mov_b64_e32 v[90:91], 0
	v_mov_b64_e32 v[92:93], 0
	v_mov_b64_e32 v[94:95], 0
	v_mov_b64_e32 v[96:97], 0
	v_mov_b64_e32 v[98:99], 0
	v_mov_b64_e32 v[100:101], 0
	v_mov_b64_e32 v[102:103], 0
	v_mov_b64_e32 v[104:105], 0
	v_mov_b64_e32 v[106:107], 0
	v_mov_b64_e32 v[108:109], 0
	v_mov_b64_e32 v[110:111], 0
	v_mov_b64_e32 v[112:113], 0
	v_mov_b64_e32 v[114:115], 0
	v_mov_b64_e32 v[116:117], 0
	v_mov_b64_e32 v[118:119], 0
	v_mov_b64_e32 v[120:121], 0
	v_mov_b64_e32 v[122:123], 0
	v_mov_b64_e32 v[124:125], 0
	v_mov_b64_e32 v[126:127], 0
	v_lshl_add_u64 v[154:155], v[154:155], 0, s[28:29]
	v_lshl_add_u64 v[158:159], v[158:159], 0, s[24:25]
	s_mov_b32 s10, 0
	.p2align	6

; template <class Epi, class Sched, bool ALIGN_EPI = false, bool SP2 = false>
; __device__ __forceinline__ void gemm_phase(PG8_LAS unsigned char* lds, const Gemm g, const Sched& S, const Epi& E) {
;     ...
; #pragma unroll
;         for (int a = 0; a < 2; ++a)
; #pragma unroll
;             for (int b = 0; b < 2; ++b)
; #pragma unroll
;                 for (int m = 0; m < 4; ++m)
; #pragma unroll
;                     for (int n = 0; n < 2; ++n) acc[a][b][m][n] = (f32x4){0.f, 0.f, 0.f, 0.f};
;         cur = nxt; cA = nA; cB = nB; ++ui;
.Lzs_8:
	v_mov_b64_e32 v[6:7], 0
	v_mov_b64_e32 v[8:9], 0
	v_mov_b64_e32 v[10:11], 0
	v_mov_b64_e32 v[12:13], 0
	v_mov_b64_e32 v[14:15], 0
	v_mov_b64_e32 v[16:17], 0
	v_mov_b64_e32 v[18:19], 0
	v_mov_b64_e32 v[20:21], 0
	v_mov_b64_e32 v[22:23], 0
	v_mov_b64_e32 v[24:25], 0
	v_mov_b64_e32 v[26:27], 0
	v_mov_b64_e32 v[28:29], 0
	v_mov_b64_e32 v[30:31], 0
	v_mov_b64_e32 v[32:33], 0
	v_mov_b64_e32 v[34:35], 0
	v_mov_b64_e32 v[36:37], 0
	v_mov_b64_e32 v[38:39], 0
	v_mov_b64_e32 v[40:41], 0
	v_mov_b64_e32 v[42:43], 0
	v_mov_b64_e32 v[44:45], 0
	v_mov_b64_e32 v[46:47], 0
	v_mov_b64_e32 v[48:49], 0
	v_mov_b64_e32 v[50:51], 0
	v_mov_b64_e32 v[52:53], 0
	v_mov_b64_e32 v[54:55], 0
	v_mov_b64_e32 v[56:57], 0
	v_mov_b64_e32 v[58:59], 0
	v_mov_b64_e32 v[60:61], 0
	v_mov_b64_e32 v[62:63], 0
	v_mov_b64_e32 v[64:65], 0
	v_mov_b64_e32 v[66:67], 0
	v_mov_b64_e32 v[68:69], 0
	v_mov_b64_e32 v[70:71], 0
	v_mov_b64_e32 v[72:73], 0
	v_mov_b64_e32 v[74:75], 0
	v_mov_b64_e32 v[76:77], 0
	v_mov_b64_e32 v[78:79], 0
	v_mov_b64_e32 v[80:81], 0
	v_mov_b64_e32 v[82:83], 0
	v_mov_b64_e32 v[84:85], 0
	v_mov_b64_e32 v[86:87], 0
	v_mov_b64_e32 v[88:89], 0
	v_mov_b64_e32 v[90:91], 0
	v_mov_b64_e32 v[92:93], 0
	v_mov_b64_e32 v[94:95], 0
	v_mov_b64_e32 v[96:97], 0
	v_mov_b64_e32 v[98:99], 0
	v_mov_b64_e32 v[100:101], 0
	v_mov_b64_e32 v[102:103], 0
	v_mov_b64_e32 v[104:105], 0
	v_mov_b64_e32 v[106:107], 0
	v_mov_b64_e32 v[108:109], 0
	v_mov_b64_e32 v[110:111], 0
	v_mov_b64_e32 v[112:113], 0
	v_mov_b64_e32 v[114:115], 0
	v_mov_b64_e32 v[116:117], 0
	v_mov_b64_e32 v[118:119], 0
	v_mov_b64_e32 v[120:121], 0
	v_mov_b64_e32 v[122:123], 0
	v_mov_b64_e32 v[124:125], 0
	v_mov_b64_e32 v[126:127], 0
	v_mov_b64_e32 v[128:129], 0
	v_mov_b64_e32 v[130:131], 0
	v_mov_b64_e32 v[132:133], 0
	v_lshl_add_u64 v[134:135], v[134:135], 0, s[26:27]
	v_lshl_add_u64 v[136:137], v[136:137], 0, s[20:21]
	s_mov_b32 s10, 0
	.p2align	6

; template <class Epi, class Sched, bool ALIGN_EPI = false, bool SP2 = false>
; __device__ __forceinline__ void gemm_phase(PG8_LAS unsigned char* lds, const Gemm g, const Sched& S, const Epi& E) {
;     ...
; #pragma unroll
;         for (int a = 0; a < 2; ++a)
; #pragma unroll
;             for (int b = 0; b < 2; ++b)
; #pragma unroll
;                 for (int m = 0; m < 4; ++m)
; #pragma unroll
;                     for (int n = 0; n < 2; ++n) acc[a][b][m][n] = (f32x4){0.f, 0.f, 0.f, 0.f};
;         cur = nxt; cA = nA; cB = nB; ++ui;
.Lzs_5:
	v_mov_b64_e32 v[0:1], 0
	v_mov_b64_e32 v[2:3], 0
	v_mov_b64_e32 v[4:5], 0
	v_mov_b64_e32 v[6:7], 0
	v_mov_b64_e32 v[8:9], 0
	v_mov_b64_e32 v[10:11], 0
	v_mov_b64_e32 v[12:13], 0
	v_mov_b64_e32 v[14:15], 0
	v_mov_b64_e32 v[16:17], 0
	v_mov_b64_e32 v[18:19], 0
	v_mov_b64_e32 v[20:21], 0
	v_mov_b64_e32 v[22:23], 0
	v_mov_b64_e32 v[24:25], 0
	v_mov_b64_e32 v[26:27], 0
	v_mov_b64_e32 v[28:29], 0
	v_mov_b64_e32 v[30:31], 0
	v_mov_b64_e32 v[32:33], 0
	v_mov_b64_e32 v[34:35], 0
	v_mov_b64_e32 v[36:37], 0
	v_mov_b64_e32 v[38:39], 0
	v_mov_b64_e32 v[40:41], 0
	v_mov_b64_e32 v[42:43], 0
	v_mov_b64_e32 v[44:45], 0
	v_mov_b64_e32 v[46:47], 0
	v_mov_b64_e32 v[48:49], 0
	v_mov_b64_e32 v[50:51], 0
	v_mov_b64_e32 v[52:53], 0
	v_mov_b64_e32 v[54:55], 0
	v_mov_b64_e32 v[56:57], 0
	v_mov_b64_e32 v[58:59], 0
	v_mov_b64_e32 v[60:61], 0
	v_mov_b64_e32 v[62:63], 0
	v_mov_b64_e32 v[64:65], 0
	v_mov_b64_e32 v[66:67], 0
	v_mov_b64_e32 v[68:69], 0
	v_mov_b64_e32 v[70:71], 0
	v_mov_b64_e32 v[72:73], 0
	v_mov_b64_e32 v[74:75], 0
	v_mov_b64_e32 v[76:77], 0
	v_mov_b64_e32 v[78:79], 0
	v_mov_b64_e32 v[80:81], 0
	v_mov_b64_e32 v[82:83], 0
	v_mov_b64_e32 v[84:85], 0
	v_mov_b64_e32 v[86:87], 0
	v_mov_b64_e32 v[88:89], 0
	v_mov_b64_e32 v[90:91], 0
	v_mov_b64_e32 v[92:93], 0
	v_mov_b64_e32 v[94:95], 0
	v_mov_b64_e32 v[96:97], 0
	v_mov_b64_e32 v[98:99], 0
	v_mov_b64_e32 v[100:101], 0
	v_mov_b64_e32 v[102:103], 0
	v_mov_b64_e32 v[104:105], 0
	v_mov_b64_e32 v[106:107], 0
	v_mov_b64_e32 v[108:109], 0
	v_mov_b64_e32 v[110:111], 0
	v_mov_b64_e32 v[112:113], 0
	v_mov_b64_e32 v[114:115], 0
	v_mov_b64_e32 v[116:117], 0
	v_mov_b64_e32 v[118:119], 0
	v_mov_b64_e32 v[120:121], 0
	v_mov_b64_e32 v[122:123], 0
	v_mov_b64_e32 v[124:125], 0
	v_mov_b64_e32 v[126:127], 0
	v_lshl_add_u64 v[128:129], v[128:129], 0, s[36:37]
	v_lshl_add_u64 v[130:131], v[130:131], 0, s[26:27]
	s_mov_b32 s10, 0
	.p2align	6
